# norm rows loop: all six wave-sum butterfly steps register-only (permlane32/16 swap + DPP), no LDS round trips
# baseline (speedup 1.0000x reference)
.LBB0_180:
	v_readlane_b32 s0, v253, 39
	s_movk_i32 s3, 0x4000
	v_add_u32_e32 v0, 0xffffc000, v50
	v_mov_b32_e32 v34, s0
	v_readlane_b32 s0, v253, 37
	v_cmp_gt_i32_e32 vcc, s3, v50
	v_min_i32_e32 v12, 0x4000, v50
	v_mov_b32_e32 v35, s0
	v_readlane_b32 s0, v253, 40
	v_cndmask_b32_e32 v3, 0, v51, vcc
	v_cndmask_b32_e32 v2, v0, v50, vcc
	v_mov_b32_e32 v36, s0
	v_readlane_b32 s0, v253, 38
	v_cndmask_b32_e32 v5, v34, v35, vcc
	v_lshlrev_b64 v[2:3], 12, v[2:3]
	v_mov_b32_e32 v37, s0
	v_cndmask_b32_e32 v4, v36, v37, vcc
	v_lshl_add_u64 v[2:3], v[4:5], 0, v[2:3]
	v_lshlrev_b32_e32 v0, 2, v52
	v_lshl_add_u64 v[2:3], v[2:3], 0, v[0:1]
	global_load_dwordx4 v[30:33], v[2:3], off
	global_load_dwordx4 v[26:29], v[2:3], off offset:1024
	s_waitcnt lgkmcnt(0)
	global_load_dwordx4 v[18:21], v[2:3], off offset:2048
	s_nop 0
	global_load_dwordx4 v[2:5], v[2:3], off offset:3072
	s_nop 0
	global_load_dwordx4 v[80:83], v[54:55], off
	v_lshl_add_u64 v[10:11], s[42:43], 0, v[50:51]
	v_ashrrev_i32_e32 v12, 11, v12
	v_readlane_b32 s0, v253, 41
	v_mov_b64_e32 v[6:7], s[36:37]
	v_lshl_add_u64 v[70:71], s[42:43], 0, v[10:11]
	v_add_u32_e32 v11, s0, v12
	s_movk_i32 s0, 0x3000
	v_mad_i64_i32 v[6:7], s[0:1], v11, s0, v[6:7]
	s_mov_b64 s[0:1], 0x1000
	s_nop 0
	v_lshl_add_u64 v[92:93], v[6:7], 0, s[0:1]
	v_lshl_add_u64 v[12:13], v[92:93], 0, v[0:1]
	global_load_dwordx4 v[84:87], v[12:13], off
	v_lshl_add_u64 v[94:95], v[6:7], 0, v[0:1]
	global_load_dwordx4 v[88:91], v[94:95], off
	v_lshl_add_u64 v[8:9], v[62:63], 0, v[58:59]
	s_mov_b32 s0, 0x133c000
	v_add_co_u32_e32 v72, vcc, s0, v8
	s_movk_i32 s2, 0x4800
	s_nop 0
	v_addc_co_u32_e32 v73, vcc, 0, v9, vcc
	v_cmp_gt_i32_e64 s[0:1], s2, v10
	v_cmp_gt_i32_e32 vcc, s2, v70
	v_mov_b32_e32 v65, v1
	v_cndmask_b32_e64 v38, v50, v10, s[0:1]
	v_ashrrev_i32_e32 v39, 31, v38
	v_add_u32_e32 v40, 0xffffc000, v38
	v_cmp_gt_i32_e64 s[4:5], s3, v38
	s_waitcnt vmcnt(6)
	v_mov_b32_e32 v8, v31
	s_waitcnt vmcnt(5)
	v_mov_b32_e32 v9, v27
	v_mov_b32_e32 v6, v30
	v_mov_b32_e32 v7, v26
	s_waitcnt vmcnt(4)
	v_mov_b32_e32 v14, v19
	s_waitcnt vmcnt(3)
	v_mov_b32_e32 v15, v3
	v_pk_mul_f32 v[8:9], v[8:9], v[8:9]
	v_mov_b32_e32 v10, v32
	v_mov_b32_e32 v11, v28
	v_mov_b32_e32 v12, v18
	v_mov_b32_e32 v13, v2
	v_pk_mul_f32 v[14:15], v[14:15], v[14:15]
	v_pk_fma_f32 v[6:7], v[6:7], v[6:7], v[8:9]
	v_mov_b32_e32 v16, v33
	v_mov_b32_e32 v17, v29
	v_mov_b32_e32 v22, v20
	v_mov_b32_e32 v23, v4
	v_pk_fma_f32 v[8:9], v[12:13], v[12:13], v[14:15]
	v_pk_fma_f32 v[6:7], v[10:11], v[10:11], v[6:7]
	v_mov_b32_e32 v24, v21
	v_mov_b32_e32 v25, v5
	v_pk_fma_f32 v[8:9], v[22:23], v[22:23], v[8:9]
	v_pk_fma_f32 v[6:7], v[16:17], v[16:17], v[6:7]
	v_pk_fma_f32 v[8:9], v[24:25], v[24:25], v[8:9]
	v_add_f32_e32 v6, v6, v7
	v_add_f32_e32 v6, v6, v8
	v_add_f32_e32 v8, v6, v9
	v_mov_b32_e32 v9, v8
	s_nop 1
	v_permlane32_swap_b32_e32 v8, v9
	v_cndmask_b32_e32 v10, v50, v70, vcc
	v_cndmask_b32_e64 v7, 0, v39, s[4:5]
	v_cndmask_b32_e64 v6, v40, v38, s[4:5]
	v_add_u32_e32 v14, 0xffffc000, v10
	s_waitcnt lgkmcnt(0)
	v_add_f32_e32 v11, v8, v9
	v_mov_b32_e32 v12, v11
	s_nop 1
	v_permlane16_swap_b32_e32 v11, v12
	v_cndmask_b32_e64 v9, v34, v35, s[4:5]
	v_cndmask_b32_e64 v8, v36, v37, s[4:5]
	v_cmp_gt_i32_e64 s[4:5], s3, v10
	v_ashrrev_i32_e32 v13, 31, v10
	s_waitcnt lgkmcnt(0)
	v_add_f32_e32 v15, v11, v12
	s_nop 1
	v_mov_b32_dpp v16, v15 row_ror:8 row_mask:0xf bank_mask:0xf
	v_cndmask_b32_e64 v10, v14, v10, s[4:5]
	v_cndmask_b32_e64 v11, 0, v13, s[4:5]
	v_lshlrev_b64 v[6:7], 12, v[6:7]
	v_lshl_add_u64 v[6:7], v[8:9], 0, v[6:7]
	s_waitcnt lgkmcnt(0)
	v_add_f32_e32 v14, v15, v16
	s_nop 1
	v_mov_b32_dpp v15, v14 row_ror:4 row_mask:0xf bank_mask:0xf
	v_lshlrev_b64 v[8:9], 12, v[10:11]
	v_cndmask_b32_e64 v13, v34, v35, s[4:5]
	v_cndmask_b32_e64 v12, v36, v37, s[4:5]
	v_lshl_add_u64 v[8:9], v[12:13], 0, v[8:9]
	s_waitcnt lgkmcnt(0)
	v_add_f32_e32 v10, v14, v15
	s_nop 1
	v_mov_b32_dpp v11, v10 quad_perm:[2,3,0,1] row_mask:0xf bank_mask:0xf
	v_lshl_add_u64 v[6:7], v[6:7], 0, v[0:1]
	v_lshl_add_u64 v[8:9], v[8:9], 0, v[0:1]
	global_load_dwordx4 v[46:49], v[6:7], off
	global_load_dwordx4 v[42:45], v[6:7], off offset:1024
	global_load_dwordx4 v[38:41], v[6:7], off offset:2048
	global_load_dwordx4 v[34:37], v[6:7], off offset:3072
	global_load_dwordx4 v[22:25], v[8:9], off
	global_load_dwordx4 v[14:17], v[8:9], off offset:1024
	s_waitcnt lgkmcnt(0)
	v_add_f32_e32 v10, v10, v11
	s_nop 1
	v_mov_b32_dpp v11, v10 quad_perm:[1,0,3,2] row_mask:0xf bank_mask:0xf
	s_waitcnt vmcnt(7)
	v_pk_add_f32 v[84:85], v[84:85], 1.0 op_sel_hi:[1,0]
	v_pk_add_f32 v[86:87], v[86:87], 1.0 op_sel_hi:[1,0]
	s_waitcnt lgkmcnt(0)
	v_add_f32_e32 v6, v10, v11
	v_fmamk_f32 v6, v6, 0x3a800000, v196
	v_mul_f32_e32 v7, 0x4b800000, v6
	v_cmp_gt_f32_e64 s[4:5], s33, v6
	s_waitcnt vmcnt(1)
	v_mul_f32_e32 v71, v23, v23
	v_cndmask_b32_e64 v6, v6, v7, s[4:5]
	v_rsq_f32_e32 v67, v6
	global_load_dwordx4 v[10:13], v[8:9], off offset:2048
	s_nop 0
	global_load_dwordx4 v[6:9], v[8:9], off offset:3072
	s_waitcnt vmcnt(2)
	v_mul_f32_e32 v79, v15, v15
	v_fmac_f32_e32 v71, v22, v22
	v_mul_f32_e32 v69, 0x45800000, v67
	v_cndmask_b32_e64 v96, v67, v69, s[4:5]
	v_pk_mul_f32 v[30:31], v[30:31], v[96:97] op_sel_hi:[1,0]
	v_pk_mul_f32 v[32:33], v[32:33], v[96:97] op_sel_hi:[1,0]
	v_pk_mul_f32 v[30:31], v[30:31], v[80:81]
	v_pk_mul_f32 v[32:33], v[32:33], v[82:83]
	v_pk_fma_f32 v[30:31], v[30:31], v[84:85], v[88:89]
	v_pk_fma_f32 v[32:33], v[32:33], v[86:87], v[90:91]
	v_cvt_pk_bf16_f32 v30, v30, v31
	v_cvt_pk_bf16_f32 v31, v32, v33
	global_store_dwordx2 v[72:73], v[30:31], off
	global_load_dwordx4 v[30:33], v[54:55], off offset:1024
	v_lshl_add_u64 v[80:81], v[92:93], 0, v[64:65]
	global_load_dwordx4 v[80:83], v[80:81], off
	s_nop 0
	global_load_dwordx4 v[84:87], v[94:95], off offset:1024
	v_pk_mul_f32 v[26:27], v[26:27], v[96:97] op_sel_hi:[1,0]
	v_pk_mul_f32 v[28:29], v[28:29], v[96:97] op_sel_hi:[1,0]
	v_mov_b32_e32 v67, v1
	v_pk_mul_f32 v[18:19], v[18:19], v[96:97] op_sel_hi:[1,0]
	v_pk_mul_f32 v[20:21], v[20:21], v[96:97] op_sel_hi:[1,0]
	v_mov_b32_e32 v69, v1
	v_fmac_f32_e32 v79, v14, v14
	v_fmac_f32_e32 v71, v24, v24
	v_fmac_f32_e32 v79, v16, v16
	v_fmac_f32_e32 v71, v25, v25
	v_fmac_f32_e32 v79, v17, v17
	v_pk_mul_f32 v[2:3], v[2:3], v[96:97] op_sel_hi:[1,0]
	v_pk_mul_f32 v[4:5], v[4:5], v[96:97] op_sel_hi:[1,0]
	s_waitcnt vmcnt(2)
	v_pk_mul_f32 v[26:27], v[26:27], v[30:31]
	v_pk_mul_f32 v[28:29], v[28:29], v[32:33]
	s_waitcnt vmcnt(1)
	v_pk_add_f32 v[30:31], v[80:81], 1.0 op_sel_hi:[1,0]
	v_pk_add_f32 v[32:33], v[82:83], 1.0 op_sel_hi:[1,0]
	s_waitcnt vmcnt(0)
	v_pk_fma_f32 v[26:27], v[26:27], v[30:31], v[84:85]
	v_pk_fma_f32 v[28:29], v[28:29], v[32:33], v[86:87]
	v_cvt_pk_bf16_f32 v26, v26, v27
	v_cvt_pk_bf16_f32 v27, v28, v29
	global_store_dwordx2 v[72:73], v[26:27], off offset:512
	global_load_dwordx4 v[26:29], v[54:55], off offset:2048
	v_lshl_add_u64 v[30:31], v[92:93], 0, v[66:67]
	global_load_dwordx4 v[30:33], v[30:31], off
	s_nop 0
	global_load_dwordx4 v[80:83], v[94:95], off offset:2048
	v_lshl_add_u64 v[84:85], v[92:93], 0, v[68:69]
	s_waitcnt vmcnt(2)
	v_pk_mul_f32 v[18:19], v[18:19], v[26:27]
	v_pk_mul_f32 v[20:21], v[20:21], v[28:29]
	s_waitcnt vmcnt(1)
	v_pk_add_f32 v[26:27], v[30:31], 1.0 op_sel_hi:[1,0]
	v_pk_add_f32 v[28:29], v[32:33], 1.0 op_sel_hi:[1,0]
	s_waitcnt vmcnt(0)
	v_pk_fma_f32 v[18:19], v[18:19], v[26:27], v[80:81]
	v_pk_fma_f32 v[20:21], v[20:21], v[28:29], v[82:83]
	v_cvt_pk_bf16_f32 v18, v18, v19
	v_cvt_pk_bf16_f32 v19, v20, v21
	global_store_dwordx2 v[72:73], v[18:19], off offset:1024
	global_load_dwordx4 v[26:29], v[54:55], off offset:3072
	global_load_dwordx4 v[30:33], v[84:85], off
	global_load_dwordx4 v[80:83], v[94:95], off offset:3072
	v_mul_f32_e32 v18, v47, v47
	v_mul_f32_e32 v19, v43, v43
	v_mul_f32_e32 v20, v39, v39
	v_fmac_f32_e32 v18, v46, v46
	v_fmac_f32_e32 v19, v42, v42
	v_mul_f32_e32 v84, v11, v11
	v_mul_f32_e32 v21, v35, v35
	v_fmac_f32_e32 v20, v38, v38
	v_mul_f32_e32 v85, v7, v7
	v_fmac_f32_e32 v18, v48, v48
	v_fmac_f32_e32 v19, v44, v44
	v_fmac_f32_e32 v84, v10, v10
	v_fmac_f32_e32 v21, v34, v34
	v_fmac_f32_e32 v20, v40, v40
	v_fmac_f32_e32 v85, v6, v6
	v_fmac_f32_e32 v18, v49, v49
	v_fmac_f32_e32 v19, v45, v45
	v_fmac_f32_e32 v84, v12, v12
	v_fmac_f32_e32 v21, v36, v36
	v_fmac_f32_e32 v20, v41, v41
	v_fmac_f32_e32 v85, v8, v8
	v_add_f32_e32 v18, v18, v19
	v_fmac_f32_e32 v84, v13, v13
	v_add_f32_e32 v19, v71, v79
	v_fmac_f32_e32 v21, v37, v37
	v_fmac_f32_e32 v85, v9, v9
	v_add_f32_e32 v18, v18, v20
	v_add_f32_e32 v19, v19, v84
	v_add_f32_e32 v18, v18, v21
	v_add_f32_e32 v19, v19, v85
	v_mov_b32_e32 v20, v18
	s_nop 1
	v_permlane32_swap_b32_e32 v18, v20
	v_mov_b32_e32 v21, v19
	s_nop 1
	v_permlane32_swap_b32_e32 v19, v21
	s_waitcnt lgkmcnt(1)
	v_add_f32_e32 v18, v18, v20
	s_waitcnt lgkmcnt(0)
	v_add_f32_e32 v19, v19, v21
	v_mov_b32_e32 v20, v18
	s_nop 1
	v_permlane16_swap_b32_e32 v18, v20
	v_mov_b32_e32 v21, v19
	s_nop 1
	v_permlane16_swap_b32_e32 v19, v21
	s_waitcnt lgkmcnt(1)
	v_add_f32_e32 v18, v18, v20
	s_waitcnt lgkmcnt(0)
	v_add_f32_e32 v19, v19, v21
	v_mov_b32_dpp v20, v18 row_ror:8 row_mask:0xf bank_mask:0xf
	s_nop 0
	v_mov_b32_dpp v21, v19 row_ror:8 row_mask:0xf bank_mask:0xf
	s_waitcnt lgkmcnt(1)
	v_add_f32_e32 v18, v18, v20
	s_waitcnt lgkmcnt(0)
	v_add_f32_e32 v19, v19, v21
	v_mov_b32_dpp v20, v18 row_ror:4 row_mask:0xf bank_mask:0xf
	s_nop 0
	v_mov_b32_dpp v21, v19 row_ror:4 row_mask:0xf bank_mask:0xf
	s_waitcnt lgkmcnt(1)
	v_add_f32_e32 v18, v18, v20
	s_waitcnt lgkmcnt(0)
	v_add_f32_e32 v19, v19, v21
	v_mov_b32_dpp v20, v18 quad_perm:[2,3,0,1] row_mask:0xf bank_mask:0xf
	s_nop 0
	v_mov_b32_dpp v21, v19 quad_perm:[2,3,0,1] row_mask:0xf bank_mask:0xf
	s_waitcnt lgkmcnt(1)
	v_add_f32_e32 v20, v18, v20
	s_waitcnt lgkmcnt(0)
	v_add_f32_e32 v18, v19, v21
	v_mov_b32_dpp v21, v20 quad_perm:[1,0,3,2] row_mask:0xf bank_mask:0xf
	s_nop 0
	v_mov_b32_dpp v19, v18 quad_perm:[1,0,3,2] row_mask:0xf bank_mask:0xf
	s_waitcnt vmcnt(2)
	v_pk_mul_f32 v[2:3], v[2:3], v[26:27]
	v_pk_mul_f32 v[4:5], v[4:5], v[28:29]
	s_waitcnt vmcnt(1)
	v_pk_add_f32 v[26:27], v[30:31], 1.0 op_sel_hi:[1,0]
	v_pk_add_f32 v[28:29], v[32:33], 1.0 op_sel_hi:[1,0]
	s_waitcnt vmcnt(0)
	v_pk_fma_f32 v[2:3], v[2:3], v[26:27], v[80:81]
	v_pk_fma_f32 v[4:5], v[4:5], v[28:29], v[82:83]
	v_cvt_pk_bf16_f32 v2, v2, v3
	v_cvt_pk_bf16_f32 v3, v4, v5
	global_store_dwordx2 v[72:73], v[2:3], off offset:1536
	s_and_saveexec_b64 s[12:13], s[0:1]
	s_cbranch_execz .LBB0_182
	v_add_u32_e32 v2, s42, v50
	v_min_i32_e32 v2, 0x4000, v2
	v_ashrrev_i32_e32 v2, 11, v2
	v_readlane_b32 s0, v253, 41
	s_waitcnt lgkmcnt(1)
	v_add_f32_e32 v71, v20, v21
	v_fmamk_f32 v71, v71, 0x3a800000, v196
	v_add_u32_e32 v4, s0, v2
	v_mov_b64_e32 v[2:3], s[36:37]
	s_movk_i32 s0, 0x3000
	v_mad_i64_i32 v[30:31], s[0:1], v4, s0, v[2:3]
	s_mov_b64 s[0:1], 0x1000
	s_nop 0
	v_lshl_add_u64 v[72:73], v[30:31], 0, s[0:1]
	v_lshl_add_u64 v[26:27], v[72:73], 0, v[0:1]
	global_load_dwordx4 v[2:5], v[54:55], off
	v_lshl_add_u64 v[80:81], v[30:31], 0, v[0:1]
	global_load_dwordx4 v[26:29], v[26:27], off
	v_mul_f32_e32 v79, 0x4b800000, v71
	global_load_dwordx4 v[30:33], v[80:81], off
	v_cmp_gt_f32_e64 s[0:1], s33, v71
	v_lshl_add_u64 v[82:83], v[72:73], 0, v[64:65]
	v_lshl_add_u64 v[20:21], v[60:61], 0, v[58:59]
	v_cndmask_b32_e64 v71, v71, v79, s[0:1]
	v_rsq_f32_e32 v71, v71
	s_mov_b32 s2, 0x133c000
	v_add_co_u32_e64 v20, s[4:5], s2, v20
	v_mul_f32_e32 v65, 0x45800000, v71
	v_cndmask_b32_e64 v84, v71, v65, s[0:1]
	v_pk_mul_f32 v[46:47], v[46:47], v[84:85] op_sel_hi:[1,0]
	v_pk_mul_f32 v[48:49], v[48:49], v[84:85] op_sel_hi:[1,0]
	v_addc_co_u32_e64 v21, s[4:5], 0, v21, s[4:5]
	v_pk_mul_f32 v[42:43], v[42:43], v[84:85] op_sel_hi:[1,0]
	v_pk_mul_f32 v[44:45], v[44:45], v[84:85] op_sel_hi:[1,0]
	v_pk_mul_f32 v[38:39], v[38:39], v[84:85] op_sel_hi:[1,0]
	v_pk_mul_f32 v[40:41], v[40:41], v[84:85] op_sel_hi:[1,0]
	v_pk_mul_f32 v[34:35], v[34:35], v[84:85] op_sel_hi:[1,0]
	v_pk_mul_f32 v[36:37], v[36:37], v[84:85] op_sel_hi:[1,0]
	s_waitcnt vmcnt(2)
	v_pk_mul_f32 v[2:3], v[46:47], v[2:3]
	v_pk_mul_f32 v[4:5], v[48:49], v[4:5]
	s_waitcnt vmcnt(1)
	v_pk_add_f32 v[26:27], v[26:27], 1.0 op_sel_hi:[1,0]
	v_pk_add_f32 v[28:29], v[28:29], 1.0 op_sel_hi:[1,0]
	s_waitcnt vmcnt(0)
	v_pk_fma_f32 v[2:3], v[2:3], v[26:27], v[30:31]
	v_pk_fma_f32 v[4:5], v[4:5], v[28:29], v[32:33]
	v_cvt_pk_bf16_f32 v2, v2, v3
	v_cvt_pk_bf16_f32 v3, v4, v5
	global_store_dwordx2 v[20:21], v[2:3], off
	global_load_dwordx4 v[2:5], v[54:55], off offset:1024
	s_nop 0
	global_load_dwordx4 v[26:29], v[82:83], off
	global_load_dwordx4 v[30:33], v[80:81], off offset:1024
	v_lshl_add_u64 v[46:47], v[72:73], 0, v[66:67]
	s_waitcnt vmcnt(2)
	v_pk_mul_f32 v[2:3], v[42:43], v[2:3]
	s_waitcnt vmcnt(1)
	v_pk_add_f32 v[26:27], v[26:27], 1.0 op_sel_hi:[1,0]
	v_pk_mul_f32 v[4:5], v[44:45], v[4:5]
	v_pk_add_f32 v[28:29], v[28:29], 1.0 op_sel_hi:[1,0]
	s_waitcnt vmcnt(0)
	v_pk_fma_f32 v[2:3], v[2:3], v[26:27], v[30:31]
	v_pk_fma_f32 v[4:5], v[4:5], v[28:29], v[32:33]
	v_cvt_pk_bf16_f32 v2, v2, v3
	v_cvt_pk_bf16_f32 v3, v4, v5
	global_store_dwordx2 v[20:21], v[2:3], off offset:512
	global_load_dwordx4 v[2:5], v[54:55], off offset:2048
	s_nop 0
	global_load_dwordx4 v[26:29], v[46:47], off
	global_load_dwordx4 v[30:33], v[80:81], off offset:2048
	v_lshl_add_u64 v[42:43], v[72:73], 0, v[68:69]
	s_waitcnt vmcnt(2)
	v_pk_mul_f32 v[2:3], v[38:39], v[2:3]
	s_waitcnt vmcnt(1)
	v_pk_add_f32 v[26:27], v[26:27], 1.0 op_sel_hi:[1,0]
	v_pk_mul_f32 v[4:5], v[40:41], v[4:5]
	v_pk_add_f32 v[28:29], v[28:29], 1.0 op_sel_hi:[1,0]
	s_waitcnt vmcnt(0)
	v_pk_fma_f32 v[2:3], v[2:3], v[26:27], v[30:31]
	v_pk_fma_f32 v[4:5], v[4:5], v[28:29], v[32:33]
	v_cvt_pk_bf16_f32 v2, v2, v3
	v_cvt_pk_bf16_f32 v3, v4, v5
	global_store_dwordx2 v[20:21], v[2:3], off offset:1024
	global_load_dwordx4 v[2:5], v[54:55], off offset:3072
	s_nop 0
	global_load_dwordx4 v[26:29], v[42:43], off
	global_load_dwordx4 v[30:33], v[80:81], off offset:3072
	s_waitcnt vmcnt(2)
	v_pk_mul_f32 v[2:3], v[34:35], v[2:3]
	s_waitcnt vmcnt(1)
	v_pk_add_f32 v[26:27], v[26:27], 1.0 op_sel_hi:[1,0]
	v_pk_mul_f32 v[4:5], v[36:37], v[4:5]
	v_pk_add_f32 v[28:29], v[28:29], 1.0 op_sel_hi:[1,0]
	s_waitcnt vmcnt(0)
	v_pk_fma_f32 v[2:3], v[2:3], v[26:27], v[30:31]
	v_pk_fma_f32 v[4:5], v[4:5], v[28:29], v[32:33]
	v_cvt_pk_bf16_f32 v2, v2, v3
	v_cvt_pk_bf16_f32 v3, v4, v5
	global_store_dwordx2 v[20:21], v[2:3], off offset:1536
